# peel + SwiGLU K-loop SGPR-base LDS-DMA addressing (no VALU in load segments) + 8-byte aligned MFMA blocks
# baseline (speedup 1.0000x reference)
; #define PG8_STAGE(bufoff, gbase, voff) do { _Pragma("unroll") for (int _i = 0; _i < 2; ++_i) \
;         __builtin_amdgcn_global_load_lds((const unsigned*)((const char*)(gbase) + (voff)[_i]), (PG8_LAS unsigned*)(lds + (bufoff) + ldsw + _i * 8192), 16, 0, 0); } while (0)
; #define PG8_LDA(dst, b, h) do { _Pragma("unroll") for (int m = 0; m < 4; ++m) _Pragma("unroll") for (int k = 0; k < 2; ++k) dst[m][k] = *(const PG8_LAS bf16x8*)(lds + PG8_SA(b, h) + aoff + m * 2048 + k * 1024); } while (0)
; #define PG8_LDB(dst, b, h) do { _Pragma("unroll") for (int n = 0; n < 2; ++n) _Pragma("unroll") for (int k = 0; k < 2; ++k) dst[n][k] = *(const PG8_LAS bf16x8*)(lds + PG8_SB(b, h) + boff + n * 2048 + k * 1024); } while (0)
; #define PG8_WAIT_V(n) asm volatile("s_waitcnt vmcnt(" #n ")" ::: "memory")
; #define PG8_WAIT_L(n) asm volatile("s_waitcnt lgkmcnt(" #n ")" ::: "memory")
; #define PG8_BAR __builtin_amdgcn_s_barrier()
; #define PG8_SCHED __builtin_amdgcn_sched_barrier(0)
; template <class Epi, class Sched, bool ALIGN_EPI = false, bool SP2 = false>
; __device__ __forceinline__ void gemm_phase(PG8_LAS unsigned char* lds, const Gemm g, const Sched& S, const Epi& E) {
;     ...
;         const bool has_next = S.next(ui + 1, nxt);
;         const char* nA = has_next ? (const char*)g.A + (size_t)nxt.pm * tstep : cA; const char* nB = has_next ? (const char*)g.Bt + (size_t)nxt.pn * tstep : cB;
;         for (int t = 0; t < nt; t += 2) {
;             const bool last = (t == nt - 2);
;             const char* a1 = cA + (size_t)(t + 1) * kstepA;
;             const char* a2 = last ? nA : cA + (size_t)(t + 2) * kstepA; const char* b2 = last ? nB : cB + (size_t)(t + 2) * kstep;
;             const char* a3 = a2 + kstepA; const char* b3 = b2 + kstep;
;             if (last && has_next) S.a_ready(nxt);
;             if constexpr (SP2) {
;             PG8_LDB(B0, 0, 0); PG8_LDB(B1, 0, 1); PG8_SCHED; PG8_LDA(At, 0, 0); PG8_STAGE(PG8_SA(1, 1), a1 + hstep, voffA);
;             PG8_WAIT_V(8); PG8_WAIT_L(0); PG8_BAR; PG8_MMA(0, 0, At, B0); PG8_MMA(0, 1, At, B1); PG8_BAR; PG8_SCHED;
;             PG8_LDA(At, 0, 1); PG8_STAGE(PG8_SB(0, 0), b2, voffB); PG8_STAGE(PG8_SB(0, 1), b2 + hstep, voffB); PG8_STAGE(PG8_SA(0, 0), a2, voffA);
;             PG8_WAIT_V(8); PG8_WAIT_L(0); PG8_BAR; PG8_MMA(1, 0, At, B0); PG8_MMA(1, 1, At, B1); PG8_BAR; PG8_SCHED;
.LBB0_408:
	s_ashr_i32 s11, s10, 31
	s_lshl_b64 s[12:13], s[10:11], 19
	s_add_u32 s12, s30, s12
	s_addc_u32 s13, s31, s13
	s_and_b64 s[18:19], s[4:5], exec
	s_cselect_b32 s11, s13, s23
	s_cselect_b32 s53, s12, s22
	s_ashr_i32 s9, s8, 31
	s_lshl_b64 s[18:19], s[8:9], 19
	s_add_u32 s18, s37, s18
	s_addc_u32 s19, s44, s19
	s_and_b64 s[26:27], s[4:5], exec
	s_cselect_b32 s9, s19, s25
	s_cselect_b32 s54, s18, s24
	s_add_u32 s55, s24, 0x100
	s_addc_u32 s56, s25, 0
	s_mov_b32 s57, -2
	s_add_u32 s24, s22, 0x8000
	s_addc_u32 s25, s23, 0
	s_cmp_eq_u32 s57, 12
	s_cselect_b32 s42, s53, s24
	s_cselect_b32 s43, s11, s25
	s_cselect_b32 s40, s54, s55
	s_cselect_b32 s41, s9, s56
	s_add_u32 s26, s42, 0x4000
	s_addc_u32 s27, s43, 0
	v_add_u32_e32 v145, s76, v142
	s_add_i32 s58, 0, 0x14000
	ds_read_b128 v[146:149], v145
	ds_read_b128 v[150:153], v145 offset:1024
	ds_read_b128 v[160:163], v145 offset:2048
	ds_read_b128 v[164:167], v145 offset:3072
	v_add_u32_e32 v145, s58, v142
	ds_read_b128 v[168:171], v145
	ds_read_b128 v[172:175], v145 offset:1024
	ds_read_b128 v[176:179], v145 offset:2048
	ds_read_b128 v[180:183], v145 offset:3072
	v_lshl_add_u64 v[230:231], s[22:23], 0, v[140:141]
	s_add_i32 m0, s45, 0xc000
	ds_read_b128 v[184:187], v144
	ds_read_b128 v[188:191], v144 offset:1024
	ds_read_b128 v[206:209], v144 offset:2048
	ds_read_b128 v[210:213], v144 offset:3072
	ds_read_b128 v[214:217], v144 offset:4096
	ds_read_b128 v[218:221], v144 offset:5120
	ds_read_b128 v[222:225], v144 offset:6144
	ds_read_b128 v[226:229], v144 offset:7168
	global_load_lds_dwordx4 v[230:231], off
	v_lshl_add_u64 v[230:231], s[22:23], 0, v[138:139]
	s_add_i32 m0, s45, 0xe000
	s_nop 0
	global_load_lds_dwordx4 v[230:231], off
	s_waitcnt vmcnt(8)
	.p2align 3
	s_waitcnt lgkmcnt(0)
	s_barrier
	v_mfma_f32_16x16x32_bf16 v[126:129], v[146:149], v[184:187], 0
	v_mfma_f32_16x16x32_bf16 v[126:129], v[150:153], v[188:191], v[126:129]
	v_mfma_f32_16x16x32_bf16 v[118:121], v[164:167], v[188:191], 0
	v_mfma_f32_16x16x32_bf16 v[118:121], v[160:163], v[184:187], v[118:121]
	v_mfma_f32_16x16x32_bf16 v[102:105], v[160:163], v[206:209], 0
	v_mfma_f32_16x16x32_bf16 v[102:105], v[164:167], v[210:213], v[102:105]
	v_mfma_f32_16x16x32_bf16 v[110:113], v[150:153], v[210:213], 0
	v_mfma_f32_16x16x32_bf16 v[110:113], v[146:149], v[206:209], v[110:113]
	v_mfma_f32_16x16x32_bf16 v[94:97], v[146:149], v[214:217], 0
	v_mfma_f32_16x16x32_bf16 v[94:97], v[150:153], v[218:221], v[94:97]
	v_mfma_f32_16x16x32_bf16 v[86:89], v[164:167], v[218:221], 0
	v_mfma_f32_16x16x32_bf16 v[86:89], v[160:163], v[214:217], v[86:89]
	v_mfma_f32_16x16x32_bf16 v[70:73], v[160:163], v[222:225], 0
	v_mfma_f32_16x16x32_bf16 v[70:73], v[164:167], v[226:229], v[70:73]
	v_mfma_f32_16x16x32_bf16 v[78:81], v[150:153], v[226:229], 0
	v_mfma_f32_16x16x32_bf16 v[78:81], v[146:149], v[222:225], v[78:81]
	v_mfma_f32_16x16x32_bf16 v[122:125], v[168:171], v[184:187], 0
	v_mfma_f32_16x16x32_bf16 v[122:125], v[172:175], v[188:191], v[122:125]
	v_mfma_f32_16x16x32_bf16 v[114:117], v[180:183], v[188:191], 0
	v_mfma_f32_16x16x32_bf16 v[114:117], v[176:179], v[184:187], v[114:117]
	v_mfma_f32_16x16x32_bf16 v[98:101], v[176:179], v[206:209], 0
	v_mfma_f32_16x16x32_bf16 v[98:101], v[180:183], v[210:213], v[98:101]
	v_mfma_f32_16x16x32_bf16 v[106:109], v[172:175], v[210:213], 0
	v_mfma_f32_16x16x32_bf16 v[106:109], v[168:171], v[206:209], v[106:109]
	v_mfma_f32_16x16x32_bf16 v[90:93], v[168:171], v[214:217], 0
	v_mfma_f32_16x16x32_bf16 v[90:93], v[172:175], v[218:221], v[90:93]
	v_mfma_f32_16x16x32_bf16 v[82:85], v[180:183], v[218:221], 0
	v_mfma_f32_16x16x32_bf16 v[82:85], v[176:179], v[214:217], v[82:85]
	v_mfma_f32_16x16x32_bf16 v[66:69], v[176:179], v[222:225], 0
	v_mfma_f32_16x16x32_bf16 v[66:69], v[180:183], v[226:229], v[66:69]
	v_mfma_f32_16x16x32_bf16 v[74:77], v[172:175], v[226:229], 0
	v_mfma_f32_16x16x32_bf16 v[74:77], v[168:171], v[222:225], v[74:77]
	s_barrier
	s_add_i32 s22, s76, s29
	v_lshl_add_u64 v[230:231], s[40:41], 0, v[0:1]
	s_mov_b32 m0, s22
	ds_read_b128 v[184:187], v144 offset:16384
	ds_read_b128 v[188:191], v144 offset:17408
	ds_read_b128 v[206:209], v144 offset:18432
	ds_read_b128 v[210:213], v144 offset:19456
	ds_read_b128 v[214:217], v144 offset:20480
	ds_read_b128 v[218:221], v144 offset:21504
	ds_read_b128 v[222:225], v144 offset:22528
	ds_read_b128 v[226:229], v144 offset:23552
	global_load_lds_dwordx4 v[230:231], off
	s_add_i32 m0, s22, 0x2000
	s_add_u32 s22, s40, 0x40000
	v_lshl_add_u64 v[232:233], s[40:41], 0, v[130:131]
	s_addc_u32 s23, s41, 0
	s_add_i32 s58, s58, s29
	global_load_lds_dwordx4 v[232:233], off
	v_lshl_add_u64 v[234:235], s[22:23], 0, v[0:1]
	s_mov_b32 m0, s58
	s_nop 0
	global_load_lds_dwordx4 v[234:235], off
	v_lshl_add_u64 v[234:235], s[22:23], 0, v[130:131]
	s_add_i32 m0, s58, 0x2000
	s_nop 0
	global_load_lds_dwordx4 v[234:235], off
	v_lshl_add_u64 v[234:235], s[42:43], 0, v[134:135]
	s_mov_b32 m0, s45
	s_nop 0
	global_load_lds_dwordx4 v[234:235], off
	v_lshl_add_u64 v[234:235], s[42:43], 0, v[132:133]
	s_mov_b32 m0, s46
	s_nop 0
	global_load_lds_dwordx4 v[234:235], off
	s_waitcnt vmcnt(8)
	.p2align 3
	s_waitcnt lgkmcnt(0)
	s_barrier
; #define PG8_STAGE(bufoff, gbase, voff) do { _Pragma("unroll") for (int _i = 0; _i < 2; ++_i) \
;         __builtin_amdgcn_global_load_lds((const unsigned*)((const char*)(gbase) + (voff)[_i]), (PG8_LAS unsigned*)(lds + (bufoff) + ldsw + _i * 8192), 16, 0, 0); } while (0)
; #define PG8_LDA(dst, b, h) do { _Pragma("unroll") for (int m = 0; m < 4; ++m) _Pragma("unroll") for (int k = 0; k < 2; ++k) dst[m][k] = *(const PG8_LAS bf16x8*)(lds + PG8_SA(b, h) + aoff + m * 2048 + k * 1024); } while (0)
; #define PG8_LDB(dst, b, h) do { _Pragma("unroll") for (int n = 0; n < 2; ++n) _Pragma("unroll") for (int k = 0; k < 2; ++k) dst[n][k] = *(const PG8_LAS bf16x8*)(lds + PG8_SB(b, h) + boff + n * 2048 + k * 1024); } while (0)
; #define PG8_MMA(ai, bj, At, Bt) do { __builtin_amdgcn_s_setprio(1); _Pragma("unroll") for (int m = 0; m < 4; ++m) _Pragma("unroll") for (int n = 0; n < 2; ++n) _Pragma("unroll") for (int k = 0; k < 2; ++k) \
;         acc[ai][bj][m][n] = __builtin_amdgcn_mfma_f32_16x16x32_bf16(Bt[n][k], At[m][k], acc[ai][bj][m][n], 0, 0, 0); __builtin_amdgcn_s_setprio(0); } while (0)
; #define PG8_WAIT_V(n) asm volatile("s_waitcnt vmcnt(" #n ")" ::: "memory")
; #define PG8_WAIT_L(n) asm volatile("s_waitcnt lgkmcnt(" #n ")" ::: "memory")
; #define PG8_BAR __builtin_amdgcn_s_barrier()
; #define PG8_SCHED __builtin_amdgcn_sched_barrier(0)
; template <class Epi, class Sched, bool ALIGN_EPI = false, bool SP2 = false>
; __device__ __forceinline__ void gemm_phase(PG8_LAS unsigned char* lds, const Gemm g, const Sched& S, const Epi& E) {
;     ...
;             PG8_WAIT_V(8); PG8_WAIT_L(0); PG8_BAR; PG8_MMA(1, 0, At, B0); PG8_MMA(1, 1, At, B1); PG8_BAR; PG8_SCHED;
;             PG8_LDB(B0, 1, 0); PG8_LDB(B1, 1, 1); PG8_SCHED; PG8_LDA(At, 1, 0); PG8_STAGE(PG8_SA(0, 1), a2 + hstep, voffA);
;             PG8_WAIT_V(8); PG8_WAIT_L(0); PG8_BAR; PG8_MMA(0, 0, At, B0); PG8_MMA(0, 1, At, B1); PG8_BAR; PG8_SCHED;
	v_mfma_f32_16x16x32_bf16 v[62:65], v[146:149], v[184:187], 0
	v_mfma_f32_16x16x32_bf16 v[62:65], v[150:153], v[188:191], v[62:65]
	v_mfma_f32_16x16x32_bf16 v[54:57], v[164:167], v[188:191], 0
	v_mfma_f32_16x16x32_bf16 v[54:57], v[160:163], v[184:187], v[54:57]
	v_mfma_f32_16x16x32_bf16 v[38:41], v[160:163], v[206:209], 0
	v_mfma_f32_16x16x32_bf16 v[38:41], v[164:167], v[210:213], v[38:41]
	v_mfma_f32_16x16x32_bf16 v[46:49], v[150:153], v[210:213], 0
	v_mfma_f32_16x16x32_bf16 v[46:49], v[146:149], v[206:209], v[46:49]
	v_mfma_f32_16x16x32_bf16 v[30:33], v[146:149], v[214:217], 0
	v_mfma_f32_16x16x32_bf16 v[30:33], v[150:153], v[218:221], v[30:33]
	v_mfma_f32_16x16x32_bf16 v[22:25], v[164:167], v[218:221], 0
	v_mfma_f32_16x16x32_bf16 v[22:25], v[160:163], v[214:217], v[22:25]
	v_mfma_f32_16x16x32_bf16 v[6:9], v[160:163], v[222:225], 0
	v_mfma_f32_16x16x32_bf16 v[6:9], v[164:167], v[226:229], v[6:9]
	v_mfma_f32_16x16x32_bf16 v[14:17], v[150:153], v[226:229], 0
	v_mfma_f32_16x16x32_bf16 v[14:17], v[146:149], v[222:225], v[14:17]
	v_mfma_f32_16x16x32_bf16 v[58:61], v[168:171], v[184:187], 0
	v_mfma_f32_16x16x32_bf16 v[58:61], v[172:175], v[188:191], v[58:61]
	v_mfma_f32_16x16x32_bf16 v[50:53], v[180:183], v[188:191], 0
	v_mfma_f32_16x16x32_bf16 v[50:53], v[176:179], v[184:187], v[50:53]
	v_mfma_f32_16x16x32_bf16 v[34:37], v[176:179], v[206:209], 0
	v_mfma_f32_16x16x32_bf16 v[34:37], v[180:183], v[210:213], v[34:37]
	v_mfma_f32_16x16x32_bf16 v[42:45], v[172:175], v[210:213], 0
	v_mfma_f32_16x16x32_bf16 v[42:45], v[168:171], v[206:209], v[42:45]
	v_mfma_f32_16x16x32_bf16 v[26:29], v[168:171], v[214:217], 0
	v_mfma_f32_16x16x32_bf16 v[26:29], v[172:175], v[218:221], v[26:29]
	v_mfma_f32_16x16x32_bf16 v[18:21], v[180:183], v[218:221], 0
	v_mfma_f32_16x16x32_bf16 v[18:21], v[176:179], v[214:217], v[18:21]
	v_mfma_f32_16x16x32_bf16 v[2:5], v[176:179], v[222:225], 0
	v_mfma_f32_16x16x32_bf16 v[2:5], v[180:183], v[226:229], v[2:5]
	v_mfma_f32_16x16x32_bf16 v[10:13], v[172:175], v[226:229], 0
	v_mfma_f32_16x16x32_bf16 v[10:13], v[168:171], v[222:225], v[10:13]
	s_barrier
	s_add_i32 s58, 0, 0x18000
	v_add_u32_e32 v145, s58, v142
	s_add_i32 s59, 0, 0x1c000
	ds_read_b128 v[146:149], v145
	ds_read_b128 v[150:153], v145 offset:1024
	ds_read_b128 v[160:163], v145 offset:2048
	ds_read_b128 v[164:167], v145 offset:3072
	v_add_u32_e32 v145, s59, v142
	ds_read_b128 v[168:171], v145
	ds_read_b128 v[172:175], v145 offset:1024
	ds_read_b128 v[176:179], v145 offset:2048
	ds_read_b128 v[180:183], v145 offset:3072
	s_add_u32 s22, s42, 0x40000
	s_addc_u32 s23, s43, 0
	s_mov_b32 m0, s47
	v_lshl_add_u64 v[234:235], s[22:23], 0, v[134:135]
	ds_read_b128 v[184:187], v144 offset:32768
	ds_read_b128 v[188:191], v144 offset:33792
	ds_read_b128 v[206:209], v144 offset:34816
	ds_read_b128 v[210:213], v144 offset:35840
	ds_read_b128 v[214:217], v144 offset:36864
	ds_read_b128 v[218:221], v144 offset:37888
	ds_read_b128 v[222:225], v144 offset:38912
	ds_read_b128 v[226:229], v144 offset:39936
	global_load_lds_dwordx4 v[234:235], off
	v_lshl_add_u64 v[234:235], s[22:23], 0, v[132:133]
	s_mov_b32 m0, s48
	s_nop 0
	global_load_lds_dwordx4 v[234:235], off
	s_waitcnt vmcnt(8)
	.p2align 3
	s_waitcnt lgkmcnt(0)
	s_barrier
	v_mfma_f32_16x16x32_bf16 v[126:129], v[146:149], v[184:187], v[126:129]
	v_mfma_f32_16x16x32_bf16 v[126:129], v[150:153], v[188:191], v[126:129]
	v_mfma_f32_16x16x32_bf16 v[118:121], v[164:167], v[188:191], v[118:121]
	v_mfma_f32_16x16x32_bf16 v[118:121], v[160:163], v[184:187], v[118:121]
	v_mfma_f32_16x16x32_bf16 v[102:105], v[160:163], v[206:209], v[102:105]
	v_mfma_f32_16x16x32_bf16 v[102:105], v[164:167], v[210:213], v[102:105]
	v_mfma_f32_16x16x32_bf16 v[110:113], v[150:153], v[210:213], v[110:113]
	v_mfma_f32_16x16x32_bf16 v[110:113], v[146:149], v[206:209], v[110:113]
	v_mfma_f32_16x16x32_bf16 v[94:97], v[146:149], v[214:217], v[94:97]
	v_mfma_f32_16x16x32_bf16 v[94:97], v[150:153], v[218:221], v[94:97]
	v_mfma_f32_16x16x32_bf16 v[86:89], v[164:167], v[218:221], v[86:89]
	v_mfma_f32_16x16x32_bf16 v[86:89], v[160:163], v[214:217], v[86:89]
	v_mfma_f32_16x16x32_bf16 v[70:73], v[160:163], v[222:225], v[70:73]
	v_mfma_f32_16x16x32_bf16 v[70:73], v[164:167], v[226:229], v[70:73]
	v_mfma_f32_16x16x32_bf16 v[78:81], v[150:153], v[226:229], v[78:81]
	v_mfma_f32_16x16x32_bf16 v[78:81], v[146:149], v[222:225], v[78:81]
	v_mfma_f32_16x16x32_bf16 v[122:125], v[168:171], v[184:187], v[122:125]
	v_mfma_f32_16x16x32_bf16 v[122:125], v[172:175], v[188:191], v[122:125]
	v_mfma_f32_16x16x32_bf16 v[114:117], v[180:183], v[188:191], v[114:117]
	v_mfma_f32_16x16x32_bf16 v[114:117], v[176:179], v[184:187], v[114:117]
	v_mfma_f32_16x16x32_bf16 v[98:101], v[176:179], v[206:209], v[98:101]
	v_mfma_f32_16x16x32_bf16 v[98:101], v[180:183], v[210:213], v[98:101]
	v_mfma_f32_16x16x32_bf16 v[106:109], v[172:175], v[210:213], v[106:109]
	v_mfma_f32_16x16x32_bf16 v[106:109], v[168:171], v[206:209], v[106:109]
	v_mfma_f32_16x16x32_bf16 v[90:93], v[168:171], v[214:217], v[90:93]
	v_mfma_f32_16x16x32_bf16 v[90:93], v[172:175], v[218:221], v[90:93]
	v_mfma_f32_16x16x32_bf16 v[82:85], v[180:183], v[218:221], v[82:85]
	v_mfma_f32_16x16x32_bf16 v[82:85], v[176:179], v[214:217], v[82:85]
	v_mfma_f32_16x16x32_bf16 v[66:69], v[176:179], v[222:225], v[66:69]
	v_mfma_f32_16x16x32_bf16 v[66:69], v[180:183], v[226:229], v[66:69]
	v_mfma_f32_16x16x32_bf16 v[74:77], v[172:175], v[226:229], v[74:77]
	v_mfma_f32_16x16x32_bf16 v[74:77], v[168:171], v[222:225], v[74:77]
	s_barrier
; #define PG8_STAGE(bufoff, gbase, voff) do { _Pragma("unroll") for (int _i = 0; _i < 2; ++_i) \
;         __builtin_amdgcn_global_load_lds((const unsigned*)((const char*)(gbase) + (voff)[_i]), (PG8_LAS unsigned*)(lds + (bufoff) + ldsw + _i * 8192), 16, 0, 0); } while (0)
; #define PG8_LDA(dst, b, h) do { _Pragma("unroll") for (int m = 0; m < 4; ++m) _Pragma("unroll") for (int k = 0; k < 2; ++k) dst[m][k] = *(const PG8_LAS bf16x8*)(lds + PG8_SA(b, h) + aoff + m * 2048 + k * 1024); } while (0)
; #define PG8_LDB(dst, b, h) do { _Pragma("unroll") for (int n = 0; n < 2; ++n) _Pragma("unroll") for (int k = 0; k < 2; ++k) dst[n][k] = *(const PG8_LAS bf16x8*)(lds + PG8_SB(b, h) + boff + n * 2048 + k * 1024); } while (0)
; #define PG8_BAR __builtin_amdgcn_s_barrier()
; template <class Epi, class Sched, bool ALIGN_EPI = false, bool SP2 = false>
; __device__ __forceinline__ void gemm_phase(PG8_LAS unsigned char* lds, const Gemm g, const Sched& S, const Epi& E) {
;     ...
;             const bool last = (t == nt - 2);
;             const char* a1 = cA + (size_t)(t + 1) * kstepA;
;             const char* a2 = last ? nA : cA + (size_t)(t + 2) * kstepA; const char* b2 = last ? nB : cB + (size_t)(t + 2) * kstep;
;             const char* a3 = a2 + kstepA; const char* b3 = b2 + kstep;
;             if (last && has_next) S.a_ready(nxt);
;             if constexpr (SP2) {
;             PG8_LDB(B0, 0, 0); PG8_LDB(B1, 0, 1); PG8_SCHED; PG8_LDA(At, 0, 0); PG8_STAGE(PG8_SA(1, 1), a1 + hstep, voffA);
;             PG8_WAIT_V(8); PG8_WAIT_L(0); PG8_BAR; PG8_MMA(0, 0, At, B0); PG8_MMA(0, 1, At, B1); PG8_BAR; PG8_SCHED;
;             PG8_LDA(At, 0, 1); PG8_STAGE(PG8_SB(0, 0), b2, voffB); PG8_STAGE(PG8_SB(0, 1), b2 + hstep, voffB); PG8_STAGE(PG8_SA(0, 0), a2, voffA);
;             PG8_WAIT_V(8); PG8_WAIT_L(0); PG8_BAR; PG8_MMA(1, 0, At, B0); PG8_MMA(1, 1, At, B1); PG8_BAR; PG8_SCHED;
;             PG8_LDB(B0, 1, 0); PG8_LDB(B1, 1, 1); PG8_SCHED; PG8_LDA(At, 1, 0); PG8_STAGE(PG8_SA(0, 1), a2 + hstep, voffA);
;             PG8_WAIT_V(8); PG8_WAIT_L(0); PG8_BAR; PG8_MMA(0, 0, At, B0); PG8_MMA(0, 1, At, B1); PG8_BAR; PG8_SCHED;
;             PG8_LDA(At, 1, 1); PG8_STAGE(PG8_SB(1, 0), b3, voffB); PG8_STAGE(PG8_SB(1, 1), b3 + hstep, voffB); PG8_STAGE(PG8_SA(1, 0), a3, voffA);
;             PG8_WAIT_V(8); PG8_WAIT_L(0); PG8_BAR; PG8_MMA(1, 0, At, B0); PG8_MMA(1, 1, At, B1); PG8_BAR; PG8_SCHED;
	s_add_i32 s22, s58, s29
	v_lshl_add_u64 v[230:231], v[230:231], 0, s[38:39]
	s_mov_b32 m0, s22
	ds_read_b128 v[184:187], v144 offset:49152
	ds_read_b128 v[188:191], v144 offset:50176
	ds_read_b128 v[206:209], v144 offset:51200
	ds_read_b128 v[210:213], v144 offset:52224
	ds_read_b128 v[214:217], v144 offset:53248
	ds_read_b128 v[218:221], v144 offset:54272
	ds_read_b128 v[222:225], v144 offset:55296
	ds_read_b128 v[226:229], v144 offset:56320
	global_load_lds_dwordx4 v[230:231], off
	s_add_i32 m0, s22, 0x2000
	s_add_u32 s22, s40, 0x40080
	v_lshl_add_u64 v[230:231], v[232:233], 0, s[38:39]
	s_addc_u32 s23, s41, 0
	s_add_i32 s40, s59, s29
	global_load_lds_dwordx4 v[230:231], off
	v_lshl_add_u64 v[230:231], s[22:23], 0, v[0:1]
	s_mov_b32 m0, s40
	s_nop 0
	global_load_lds_dwordx4 v[230:231], off
	v_lshl_add_u64 v[230:231], s[22:23], 0, v[130:131]
	s_add_i32 m0, s40, 0x2000
	s_nop 0
	global_load_lds_dwordx4 v[230:231], off
	v_lshl_add_u64 v[230:231], s[26:27], 0, v[134:135]
	s_mov_b32 m0, s49
	s_nop 0
	global_load_lds_dwordx4 v[230:231], off
	v_lshl_add_u64 v[230:231], s[26:27], 0, v[132:133]
	s_mov_b32 m0, s50
	s_nop 0
	global_load_lds_dwordx4 v[230:231], off
	s_waitcnt vmcnt(8)
	.p2align 3
	s_waitcnt lgkmcnt(0)
	s_barrier
	v_mfma_f32_16x16x32_bf16 v[62:65], v[146:149], v[184:187], v[62:65]
	v_mfma_f32_16x16x32_bf16 v[62:65], v[150:153], v[188:191], v[62:65]
	v_mfma_f32_16x16x32_bf16 v[54:57], v[164:167], v[188:191], v[54:57]
	v_mfma_f32_16x16x32_bf16 v[54:57], v[160:163], v[184:187], v[54:57]
	v_mfma_f32_16x16x32_bf16 v[38:41], v[160:163], v[206:209], v[38:41]
	v_mfma_f32_16x16x32_bf16 v[38:41], v[164:167], v[210:213], v[38:41]
	v_mfma_f32_16x16x32_bf16 v[46:49], v[150:153], v[210:213], v[46:49]
	v_mfma_f32_16x16x32_bf16 v[46:49], v[146:149], v[206:209], v[46:49]
	v_mfma_f32_16x16x32_bf16 v[30:33], v[146:149], v[214:217], v[30:33]
	v_mfma_f32_16x16x32_bf16 v[30:33], v[150:153], v[218:221], v[30:33]
	v_mfma_f32_16x16x32_bf16 v[22:25], v[164:167], v[218:221], v[22:25]
	v_mfma_f32_16x16x32_bf16 v[22:25], v[160:163], v[214:217], v[22:25]
	v_mfma_f32_16x16x32_bf16 v[6:9], v[160:163], v[222:225], v[6:9]
	v_mfma_f32_16x16x32_bf16 v[6:9], v[164:167], v[226:229], v[6:9]
	v_mfma_f32_16x16x32_bf16 v[14:17], v[150:153], v[226:229], v[14:17]
	v_mfma_f32_16x16x32_bf16 v[14:17], v[146:149], v[222:225], v[14:17]
	v_mfma_f32_16x16x32_bf16 v[58:61], v[168:171], v[184:187], v[58:61]
	v_mfma_f32_16x16x32_bf16 v[58:61], v[172:175], v[188:191], v[58:61]
	v_mfma_f32_16x16x32_bf16 v[50:53], v[180:183], v[188:191], v[50:53]
	v_mfma_f32_16x16x32_bf16 v[50:53], v[176:179], v[184:187], v[50:53]
	v_mfma_f32_16x16x32_bf16 v[34:37], v[176:179], v[206:209], v[34:37]
	v_mfma_f32_16x16x32_bf16 v[34:37], v[180:183], v[210:213], v[34:37]
	v_mfma_f32_16x16x32_bf16 v[42:45], v[172:175], v[210:213], v[42:45]
	v_mfma_f32_16x16x32_bf16 v[42:45], v[168:171], v[206:209], v[42:45]
	v_mfma_f32_16x16x32_bf16 v[26:29], v[168:171], v[214:217], v[26:29]
	v_mfma_f32_16x16x32_bf16 v[26:29], v[172:175], v[218:221], v[26:29]
	v_mfma_f32_16x16x32_bf16 v[18:21], v[180:183], v[218:221], v[18:21]
	v_mfma_f32_16x16x32_bf16 v[18:21], v[176:179], v[214:217], v[18:21]
	v_mfma_f32_16x16x32_bf16 v[2:5], v[176:179], v[222:225], v[2:5]
	v_mfma_f32_16x16x32_bf16 v[2:5], v[180:183], v[226:229], v[2:5]
	v_mfma_f32_16x16x32_bf16 v[10:13], v[172:175], v[226:229], v[10:13]
	v_mfma_f32_16x16x32_bf16 v[10:13], v[168:171], v[222:225], v[10:13]
	s_barrier
	s_add_i32 s57, s57, 2
	s_add_u32 s55, s55, 0x100
	s_addc_u32 s56, s56, 0
	s_cmp_gt_u32 s57, 13
	s_mov_b64 s[22:23], s[24:25]
	s_cbranch_scc1 .Lpeel_exit_2
	v_add_u32_e32 v145, s76, v142
.LBB0_409:
	s_add_u32 s24, s22, 0x8000
	s_addc_u32 s25, s23, 0
	s_cmp_eq_u32 s57, 12
	s_cselect_b32 s42, s53, s24
	s_cselect_b32 s43, s11, s25
	s_cselect_b32 s40, s54, s55
	s_cselect_b32 s41, s9, s56
	s_add_u32 s26, s42, 0x4000
	s_addc_u32 s27, s43, 0
	ds_read_b128 v[146:149], v145
	ds_read_b128 v[150:153], v145 offset:1024
	ds_read_b128 v[160:163], v145 offset:2048
	ds_read_b128 v[164:167], v145 offset:3072
	ds_read_b128 v[168:171], v145 offset:16384
	ds_read_b128 v[172:175], v145 offset:17408
	ds_read_b128 v[176:179], v145 offset:18432
	ds_read_b128 v[180:183], v145 offset:19456
	s_add_i32 m0, s45, 0xc000
	ds_read_b128 v[184:187], v144
	ds_read_b128 v[188:191], v144 offset:1024
	ds_read_b128 v[206:209], v144 offset:2048
	ds_read_b128 v[210:213], v144 offset:3072
	ds_read_b128 v[214:217], v144 offset:4096
	ds_read_b128 v[218:221], v144 offset:5120
	ds_read_b128 v[222:225], v144 offset:6144
	ds_read_b128 v[226:229], v144 offset:7168
	global_load_lds_dwordx4 v140, s[22:23]
	s_add_i32 m0, s45, 0xe000
	s_nop 0
	global_load_lds_dwordx4 v138, s[22:23]
	s_waitcnt vmcnt(8)
	.p2align 3
	s_waitcnt lgkmcnt(0)
	s_barrier
; #define PG8_STAGE(bufoff, gbase, voff) do { _Pragma("unroll") for (int _i = 0; _i < 2; ++_i) \
;         __builtin_amdgcn_global_load_lds((const unsigned*)((const char*)(gbase) + (voff)[_i]), (PG8_LAS unsigned*)(lds + (bufoff) + ldsw + _i * 8192), 16, 0, 0); } while (0)
; #define PG8_LDA(dst, b, h) do { _Pragma("unroll") for (int m = 0; m < 4; ++m) _Pragma("unroll") for (int k = 0; k < 2; ++k) dst[m][k] = *(const PG8_LAS bf16x8*)(lds + PG8_SA(b, h) + aoff + m * 2048 + k * 1024); } while (0)
; #define PG8_MMA(ai, bj, At, Bt) do { __builtin_amdgcn_s_setprio(1); _Pragma("unroll") for (int m = 0; m < 4; ++m) _Pragma("unroll") for (int n = 0; n < 2; ++n) _Pragma("unroll") for (int k = 0; k < 2; ++k) \
;         acc[ai][bj][m][n] = __builtin_amdgcn_mfma_f32_16x16x32_bf16(Bt[n][k], At[m][k], acc[ai][bj][m][n], 0, 0, 0); __builtin_amdgcn_s_setprio(0); } while (0)
; #define PG8_WAIT_V(n) asm volatile("s_waitcnt vmcnt(" #n ")" ::: "memory")
; #define PG8_WAIT_L(n) asm volatile("s_waitcnt lgkmcnt(" #n ")" ::: "memory")
; #define PG8_BAR __builtin_amdgcn_s_barrier()
; #define PG8_SCHED __builtin_amdgcn_sched_barrier(0)
; template <class Epi, class Sched, bool ALIGN_EPI = false, bool SP2 = false>
; __device__ __forceinline__ void gemm_phase(PG8_LAS unsigned char* lds, const Gemm g, const Sched& S, const Epi& E) {
;     ...
;             PG8_WAIT_V(8); PG8_WAIT_L(0); PG8_BAR; PG8_MMA(0, 0, At, B0); PG8_MMA(0, 1, At, B1); PG8_BAR; PG8_SCHED;
;             PG8_LDA(At, 0, 1); PG8_STAGE(PG8_SB(0, 0), b2, voffB); PG8_STAGE(PG8_SB(0, 1), b2 + hstep, voffB); PG8_STAGE(PG8_SA(0, 0), a2, voffA);
;             PG8_WAIT_V(8); PG8_WAIT_L(0); PG8_BAR; PG8_MMA(1, 0, At, B0); PG8_MMA(1, 1, At, B1); PG8_BAR; PG8_SCHED;
	v_mfma_f32_16x16x32_bf16 v[126:129], v[146:149], v[184:187], v[126:129]
	v_mfma_f32_16x16x32_bf16 v[126:129], v[150:153], v[188:191], v[126:129]
	v_mfma_f32_16x16x32_bf16 v[118:121], v[164:167], v[188:191], v[118:121]
	v_mfma_f32_16x16x32_bf16 v[118:121], v[160:163], v[184:187], v[118:121]
	v_mfma_f32_16x16x32_bf16 v[102:105], v[160:163], v[206:209], v[102:105]
	v_mfma_f32_16x16x32_bf16 v[102:105], v[164:167], v[210:213], v[102:105]
	v_mfma_f32_16x16x32_bf16 v[110:113], v[150:153], v[210:213], v[110:113]
	v_mfma_f32_16x16x32_bf16 v[110:113], v[146:149], v[206:209], v[110:113]
	v_mfma_f32_16x16x32_bf16 v[94:97], v[146:149], v[214:217], v[94:97]
	v_mfma_f32_16x16x32_bf16 v[94:97], v[150:153], v[218:221], v[94:97]
	v_mfma_f32_16x16x32_bf16 v[86:89], v[164:167], v[218:221], v[86:89]
	v_mfma_f32_16x16x32_bf16 v[86:89], v[160:163], v[214:217], v[86:89]
	v_mfma_f32_16x16x32_bf16 v[70:73], v[160:163], v[222:225], v[70:73]
	v_mfma_f32_16x16x32_bf16 v[70:73], v[164:167], v[226:229], v[70:73]
	v_mfma_f32_16x16x32_bf16 v[78:81], v[150:153], v[226:229], v[78:81]
	v_mfma_f32_16x16x32_bf16 v[78:81], v[146:149], v[222:225], v[78:81]
	v_mfma_f32_16x16x32_bf16 v[122:125], v[168:171], v[184:187], v[122:125]
	v_mfma_f32_16x16x32_bf16 v[122:125], v[172:175], v[188:191], v[122:125]
	v_mfma_f32_16x16x32_bf16 v[114:117], v[180:183], v[188:191], v[114:117]
	v_mfma_f32_16x16x32_bf16 v[114:117], v[176:179], v[184:187], v[114:117]
	v_mfma_f32_16x16x32_bf16 v[98:101], v[176:179], v[206:209], v[98:101]
	v_mfma_f32_16x16x32_bf16 v[98:101], v[180:183], v[210:213], v[98:101]
	v_mfma_f32_16x16x32_bf16 v[106:109], v[172:175], v[210:213], v[106:109]
	v_mfma_f32_16x16x32_bf16 v[106:109], v[168:171], v[206:209], v[106:109]
	v_mfma_f32_16x16x32_bf16 v[90:93], v[168:171], v[214:217], v[90:93]
	v_mfma_f32_16x16x32_bf16 v[90:93], v[172:175], v[218:221], v[90:93]
	v_mfma_f32_16x16x32_bf16 v[82:85], v[180:183], v[218:221], v[82:85]
	v_mfma_f32_16x16x32_bf16 v[82:85], v[176:179], v[214:217], v[82:85]
	v_mfma_f32_16x16x32_bf16 v[66:69], v[176:179], v[222:225], v[66:69]
	v_mfma_f32_16x16x32_bf16 v[66:69], v[180:183], v[226:229], v[66:69]
	v_mfma_f32_16x16x32_bf16 v[74:77], v[172:175], v[226:229], v[74:77]
	v_mfma_f32_16x16x32_bf16 v[74:77], v[168:171], v[222:225], v[74:77]
	s_barrier
	s_add_i32 s58, s76, s29
	s_mov_b32 m0, s58
	ds_read_b128 v[184:187], v144 offset:16384
	ds_read_b128 v[188:191], v144 offset:17408
	ds_read_b128 v[206:209], v144 offset:18432
	ds_read_b128 v[210:213], v144 offset:19456
	ds_read_b128 v[214:217], v144 offset:20480
	ds_read_b128 v[218:221], v144 offset:21504
	ds_read_b128 v[222:225], v144 offset:22528
	ds_read_b128 v[226:229], v144 offset:23552
	global_load_lds_dwordx4 v0, s[40:41]
	s_add_i32 m0, s58, 0x2000
	s_add_u32 s22, s40, 0x40000
	s_addc_u32 s23, s41, 0
	global_load_lds_dwordx4 v130, s[40:41]
	s_add_i32 m0, s58, 0x4000
	s_nop 0
	global_load_lds_dwordx4 v0, s[22:23]
	s_add_i32 m0, s58, 0x6000
	s_nop 0
	global_load_lds_dwordx4 v130, s[22:23]
	s_mov_b32 m0, s45
	s_nop 0
	global_load_lds_dwordx4 v134, s[42:43]
	s_mov_b32 m0, s46
	s_nop 0
	global_load_lds_dwordx4 v132, s[42:43]
	s_waitcnt vmcnt(8)
	.p2align 3
	s_waitcnt lgkmcnt(0)
	s_barrier
	v_mfma_f32_16x16x32_bf16 v[62:65], v[146:149], v[184:187], v[62:65]
	v_mfma_f32_16x16x32_bf16 v[62:65], v[150:153], v[188:191], v[62:65]
	v_mfma_f32_16x16x32_bf16 v[54:57], v[164:167], v[188:191], v[54:57]
	v_mfma_f32_16x16x32_bf16 v[54:57], v[160:163], v[184:187], v[54:57]
	v_mfma_f32_16x16x32_bf16 v[38:41], v[160:163], v[206:209], v[38:41]
	v_mfma_f32_16x16x32_bf16 v[38:41], v[164:167], v[210:213], v[38:41]
	v_mfma_f32_16x16x32_bf16 v[46:49], v[150:153], v[210:213], v[46:49]
	v_mfma_f32_16x16x32_bf16 v[46:49], v[146:149], v[206:209], v[46:49]
	v_mfma_f32_16x16x32_bf16 v[30:33], v[146:149], v[214:217], v[30:33]
	v_mfma_f32_16x16x32_bf16 v[30:33], v[150:153], v[218:221], v[30:33]
	v_mfma_f32_16x16x32_bf16 v[22:25], v[164:167], v[218:221], v[22:25]
	v_mfma_f32_16x16x32_bf16 v[22:25], v[160:163], v[214:217], v[22:25]
	v_mfma_f32_16x16x32_bf16 v[6:9], v[160:163], v[222:225], v[6:9]
	v_mfma_f32_16x16x32_bf16 v[6:9], v[164:167], v[226:229], v[6:9]
	v_mfma_f32_16x16x32_bf16 v[14:17], v[150:153], v[226:229], v[14:17]
	v_mfma_f32_16x16x32_bf16 v[14:17], v[146:149], v[222:225], v[14:17]
	v_mfma_f32_16x16x32_bf16 v[58:61], v[168:171], v[184:187], v[58:61]
	v_mfma_f32_16x16x32_bf16 v[58:61], v[172:175], v[188:191], v[58:61]
	v_mfma_f32_16x16x32_bf16 v[50:53], v[180:183], v[188:191], v[50:53]
	v_mfma_f32_16x16x32_bf16 v[50:53], v[176:179], v[184:187], v[50:53]
	v_mfma_f32_16x16x32_bf16 v[34:37], v[176:179], v[206:209], v[34:37]
	v_mfma_f32_16x16x32_bf16 v[34:37], v[180:183], v[210:213], v[34:37]
	v_mfma_f32_16x16x32_bf16 v[42:45], v[172:175], v[210:213], v[42:45]
	v_mfma_f32_16x16x32_bf16 v[42:45], v[168:171], v[206:209], v[42:45]
	v_mfma_f32_16x16x32_bf16 v[26:29], v[168:171], v[214:217], v[26:29]
	v_mfma_f32_16x16x32_bf16 v[26:29], v[172:175], v[218:221], v[26:29]
	v_mfma_f32_16x16x32_bf16 v[18:21], v[180:183], v[218:221], v[18:21]
	v_mfma_f32_16x16x32_bf16 v[18:21], v[176:179], v[214:217], v[18:21]
	v_mfma_f32_16x16x32_bf16 v[2:5], v[176:179], v[222:225], v[2:5]
	v_mfma_f32_16x16x32_bf16 v[2:5], v[180:183], v[226:229], v[2:5]
	v_mfma_f32_16x16x32_bf16 v[10:13], v[172:175], v[226:229], v[10:13]
	v_mfma_f32_16x16x32_bf16 v[10:13], v[168:171], v[222:225], v[10:13]
	s_barrier
; #define PG8_STAGE(bufoff, gbase, voff) do { _Pragma("unroll") for (int _i = 0; _i < 2; ++_i) \
;         __builtin_amdgcn_global_load_lds((const unsigned*)((const char*)(gbase) + (voff)[_i]), (PG8_LAS unsigned*)(lds + (bufoff) + ldsw + _i * 8192), 16, 0, 0); } while (0)
; #define PG8_LDA(dst, b, h) do { _Pragma("unroll") for (int m = 0; m < 4; ++m) _Pragma("unroll") for (int k = 0; k < 2; ++k) dst[m][k] = *(const PG8_LAS bf16x8*)(lds + PG8_SA(b, h) + aoff + m * 2048 + k * 1024); } while (0)
; #define PG8_LDB(dst, b, h) do { _Pragma("unroll") for (int n = 0; n < 2; ++n) _Pragma("unroll") for (int k = 0; k < 2; ++k) dst[n][k] = *(const PG8_LAS bf16x8*)(lds + PG8_SB(b, h) + boff + n * 2048 + k * 1024); } while (0)
; #define PG8_MMA(ai, bj, At, Bt) do { __builtin_amdgcn_s_setprio(1); _Pragma("unroll") for (int m = 0; m < 4; ++m) _Pragma("unroll") for (int n = 0; n < 2; ++n) _Pragma("unroll") for (int k = 0; k < 2; ++k) \
;         acc[ai][bj][m][n] = __builtin_amdgcn_mfma_f32_16x16x32_bf16(Bt[n][k], At[m][k], acc[ai][bj][m][n], 0, 0, 0); __builtin_amdgcn_s_setprio(0); } while (0)
; #define PG8_WAIT_V(n) asm volatile("s_waitcnt vmcnt(" #n ")" ::: "memory")
; #define PG8_WAIT_L(n) asm volatile("s_waitcnt lgkmcnt(" #n ")" ::: "memory")
; #define PG8_BAR __builtin_amdgcn_s_barrier()
; #define PG8_SCHED __builtin_amdgcn_sched_barrier(0)
; template <class Epi, class Sched, bool ALIGN_EPI = false, bool SP2 = false>
; __device__ __forceinline__ void gemm_phase(PG8_LAS unsigned char* lds, const Gemm g, const Sched& S, const Epi& E) {
;     ...
;             PG8_LDB(B0, 1, 0); PG8_LDB(B1, 1, 1); PG8_SCHED; PG8_LDA(At, 1, 0); PG8_STAGE(PG8_SA(0, 1), a2 + hstep, voffA);
;             PG8_WAIT_V(8); PG8_WAIT_L(0); PG8_BAR; PG8_MMA(0, 0, At, B0); PG8_MMA(0, 1, At, B1); PG8_BAR; PG8_SCHED;
;             PG8_LDA(At, 1, 1); PG8_STAGE(PG8_SB(1, 0), b3, voffB); PG8_STAGE(PG8_SB(1, 1), b3 + hstep, voffB); PG8_STAGE(PG8_SA(1, 0), a3, voffA);
;             PG8_WAIT_V(8); PG8_WAIT_L(0); PG8_BAR; PG8_MMA(1, 0, At, B0); PG8_MMA(1, 1, At, B1); PG8_BAR; PG8_SCHED;
	ds_read_b128 v[146:149], v145 offset:32768
	ds_read_b128 v[150:153], v145 offset:33792
	ds_read_b128 v[160:163], v145 offset:34816
	ds_read_b128 v[164:167], v145 offset:35840
	ds_read_b128 v[168:171], v145 offset:49152
	ds_read_b128 v[172:175], v145 offset:50176
	ds_read_b128 v[176:179], v145 offset:51200
	ds_read_b128 v[180:183], v145 offset:52224
	s_add_u32 s22, s42, 0x40000
	s_addc_u32 s23, s43, 0
	s_mov_b32 m0, s47
	ds_read_b128 v[184:187], v144 offset:32768
	ds_read_b128 v[188:191], v144 offset:33792
	ds_read_b128 v[206:209], v144 offset:34816
	ds_read_b128 v[210:213], v144 offset:35840
	ds_read_b128 v[214:217], v144 offset:36864
	ds_read_b128 v[218:221], v144 offset:37888
	ds_read_b128 v[222:225], v144 offset:38912
	ds_read_b128 v[226:229], v144 offset:39936
	global_load_lds_dwordx4 v134, s[22:23]
	s_mov_b32 m0, s48
	s_nop 0
	global_load_lds_dwordx4 v132, s[22:23]
	s_waitcnt vmcnt(8)
	.p2align 3
	s_waitcnt lgkmcnt(0)
	s_barrier
	v_mfma_f32_16x16x32_bf16 v[126:129], v[146:149], v[184:187], v[126:129]
	v_mfma_f32_16x16x32_bf16 v[126:129], v[150:153], v[188:191], v[126:129]
	v_mfma_f32_16x16x32_bf16 v[118:121], v[164:167], v[188:191], v[118:121]
	v_mfma_f32_16x16x32_bf16 v[118:121], v[160:163], v[184:187], v[118:121]
	v_mfma_f32_16x16x32_bf16 v[102:105], v[160:163], v[206:209], v[102:105]
	v_mfma_f32_16x16x32_bf16 v[102:105], v[164:167], v[210:213], v[102:105]
	v_mfma_f32_16x16x32_bf16 v[110:113], v[150:153], v[210:213], v[110:113]
	v_mfma_f32_16x16x32_bf16 v[110:113], v[146:149], v[206:209], v[110:113]
	v_mfma_f32_16x16x32_bf16 v[94:97], v[146:149], v[214:217], v[94:97]
	v_mfma_f32_16x16x32_bf16 v[94:97], v[150:153], v[218:221], v[94:97]
	v_mfma_f32_16x16x32_bf16 v[86:89], v[164:167], v[218:221], v[86:89]
	v_mfma_f32_16x16x32_bf16 v[86:89], v[160:163], v[214:217], v[86:89]
	v_mfma_f32_16x16x32_bf16 v[70:73], v[160:163], v[222:225], v[70:73]
	v_mfma_f32_16x16x32_bf16 v[70:73], v[164:167], v[226:229], v[70:73]
	v_mfma_f32_16x16x32_bf16 v[78:81], v[150:153], v[226:229], v[78:81]
	v_mfma_f32_16x16x32_bf16 v[78:81], v[146:149], v[222:225], v[78:81]
	v_mfma_f32_16x16x32_bf16 v[122:125], v[168:171], v[184:187], v[122:125]
	v_mfma_f32_16x16x32_bf16 v[122:125], v[172:175], v[188:191], v[122:125]
	v_mfma_f32_16x16x32_bf16 v[114:117], v[180:183], v[188:191], v[114:117]
	v_mfma_f32_16x16x32_bf16 v[114:117], v[176:179], v[184:187], v[114:117]
	v_mfma_f32_16x16x32_bf16 v[98:101], v[176:179], v[206:209], v[98:101]
	v_mfma_f32_16x16x32_bf16 v[98:101], v[180:183], v[210:213], v[98:101]
	v_mfma_f32_16x16x32_bf16 v[106:109], v[172:175], v[210:213], v[106:109]
	v_mfma_f32_16x16x32_bf16 v[106:109], v[168:171], v[206:209], v[106:109]
	v_mfma_f32_16x16x32_bf16 v[90:93], v[168:171], v[214:217], v[90:93]
	v_mfma_f32_16x16x32_bf16 v[90:93], v[172:175], v[218:221], v[90:93]
	v_mfma_f32_16x16x32_bf16 v[82:85], v[180:183], v[218:221], v[82:85]
	v_mfma_f32_16x16x32_bf16 v[82:85], v[176:179], v[214:217], v[82:85]
	v_mfma_f32_16x16x32_bf16 v[66:69], v[176:179], v[222:225], v[66:69]
	v_mfma_f32_16x16x32_bf16 v[66:69], v[180:183], v[226:229], v[66:69]
	v_mfma_f32_16x16x32_bf16 v[74:77], v[172:175], v[226:229], v[74:77]
	v_mfma_f32_16x16x32_bf16 v[74:77], v[168:171], v[222:225], v[74:77]
	s_barrier
	s_add_u32 s22, s40, 0x80
	s_addc_u32 s23, s41, 0
	s_add_i32 s58, s29, 0x18000
	s_mov_b32 m0, s58
	ds_read_b128 v[184:187], v144 offset:49152
	ds_read_b128 v[188:191], v144 offset:50176
	ds_read_b128 v[206:209], v144 offset:51200
	ds_read_b128 v[210:213], v144 offset:52224
	ds_read_b128 v[214:217], v144 offset:53248
	ds_read_b128 v[218:221], v144 offset:54272
	ds_read_b128 v[222:225], v144 offset:55296
	ds_read_b128 v[226:229], v144 offset:56320
	global_load_lds_dwordx4 v0, s[22:23]
	s_add_i32 m0, s58, 0x2000
	s_add_u32 s40, s22, 0x40000
	s_addc_u32 s41, s23, 0
	global_load_lds_dwordx4 v130, s[22:23]
	s_add_i32 m0, s58, 0x4000
	s_nop 0
	global_load_lds_dwordx4 v0, s[40:41]
	s_add_i32 m0, s58, 0x6000
	s_nop 0
	global_load_lds_dwordx4 v130, s[40:41]
	s_mov_b32 m0, s49
	s_nop 0
	global_load_lds_dwordx4 v134, s[26:27]
	s_mov_b32 m0, s50
	s_nop 0
	global_load_lds_dwordx4 v132, s[26:27]
	s_waitcnt vmcnt(8)
	.p2align 3
	s_waitcnt lgkmcnt(0)
	s_barrier
	v_mfma_f32_16x16x32_bf16 v[62:65], v[146:149], v[184:187], v[62:65]
	v_mfma_f32_16x16x32_bf16 v[62:65], v[150:153], v[188:191], v[62:65]
	v_mfma_f32_16x16x32_bf16 v[54:57], v[164:167], v[188:191], v[54:57]
	v_mfma_f32_16x16x32_bf16 v[54:57], v[160:163], v[184:187], v[54:57]
	v_mfma_f32_16x16x32_bf16 v[38:41], v[160:163], v[206:209], v[38:41]
	v_mfma_f32_16x16x32_bf16 v[38:41], v[164:167], v[210:213], v[38:41]
	v_mfma_f32_16x16x32_bf16 v[46:49], v[150:153], v[210:213], v[46:49]
	v_mfma_f32_16x16x32_bf16 v[46:49], v[146:149], v[206:209], v[46:49]
	v_mfma_f32_16x16x32_bf16 v[30:33], v[146:149], v[214:217], v[30:33]
	v_mfma_f32_16x16x32_bf16 v[30:33], v[150:153], v[218:221], v[30:33]
	v_mfma_f32_16x16x32_bf16 v[22:25], v[164:167], v[218:221], v[22:25]
	v_mfma_f32_16x16x32_bf16 v[22:25], v[160:163], v[214:217], v[22:25]
	v_mfma_f32_16x16x32_bf16 v[6:9], v[160:163], v[222:225], v[6:9]
	v_mfma_f32_16x16x32_bf16 v[6:9], v[164:167], v[226:229], v[6:9]
	v_mfma_f32_16x16x32_bf16 v[14:17], v[150:153], v[226:229], v[14:17]
	v_mfma_f32_16x16x32_bf16 v[14:17], v[146:149], v[222:225], v[14:17]
	v_mfma_f32_16x16x32_bf16 v[58:61], v[168:171], v[184:187], v[58:61]
	v_mfma_f32_16x16x32_bf16 v[58:61], v[172:175], v[188:191], v[58:61]
	v_mfma_f32_16x16x32_bf16 v[50:53], v[180:183], v[188:191], v[50:53]
	v_mfma_f32_16x16x32_bf16 v[50:53], v[176:179], v[184:187], v[50:53]
	v_mfma_f32_16x16x32_bf16 v[34:37], v[176:179], v[206:209], v[34:37]
	v_mfma_f32_16x16x32_bf16 v[34:37], v[180:183], v[210:213], v[34:37]
	v_mfma_f32_16x16x32_bf16 v[42:45], v[172:175], v[210:213], v[42:45]
	v_mfma_f32_16x16x32_bf16 v[42:45], v[168:171], v[206:209], v[42:45]
	v_mfma_f32_16x16x32_bf16 v[26:29], v[168:171], v[214:217], v[26:29]
	v_mfma_f32_16x16x32_bf16 v[26:29], v[172:175], v[218:221], v[26:29]
	v_mfma_f32_16x16x32_bf16 v[18:21], v[180:183], v[218:221], v[18:21]
	v_mfma_f32_16x16x32_bf16 v[18:21], v[176:179], v[214:217], v[18:21]
	v_mfma_f32_16x16x32_bf16 v[2:5], v[176:179], v[222:225], v[2:5]
	v_mfma_f32_16x16x32_bf16 v[2:5], v[180:183], v[226:229], v[2:5]
	v_mfma_f32_16x16x32_bf16 v[10:13], v[172:175], v[226:229], v[10:13]
	v_mfma_f32_16x16x32_bf16 v[10:13], v[168:171], v[222:225], v[10:13]
	s_barrier
	s_add_i32 s57, s57, 2
	s_add_u32 s55, s55, 0x100
	s_addc_u32 s56, s56, 0
	s_cmp_gt_u32 s57, 13
	s_mov_b64 s[22:23], s[24:25]
	s_cbranch_scc0 .LBB0_409
